# prologue/epilogue de-serialisation extended: 8th gMLP U-row load batched with the other seven; first K-iteration peeled (C=0 MFMAs) in the in-proj A/B and memory-KV GEMM loops too
# baseline (speedup 1.0000x reference)
.LBB0_213:
	s_lshl_b32 s24, s24, 7
	s_ashr_i32 s25, s24, 31
	s_mul_i32 s34, s6, 0x600
	s_mul_hi_i32 s8, s6, 0x600
	s_add_u32 s34, s36, s34
	s_addc_u32 s8, s37, s8
	s_lshl_b64 s[6:7], s[6:7], 11
	s_add_u32 s35, s79, s6
	s_addc_u32 s39, s80, s7
	s_lshl_b64 s[6:7], s[24:25], 2
	s_add_u32 s42, s2, s6
	s_addc_u32 s43, s3, s7
	s_add_u32 s6, s40, s47
	s_addc_u32 s7, s41, 0
	s_lshl_b64 s[2:3], s[16:17], 2
	s_add_u32 s24, s6, s2
	s_addc_u32 s25, s7, s3
	s_lshl_b64 s[6:7], s[16:17], 1
	s_add_u32 s2, s34, s6
	s_addc_u32 s3, s8, s7
	s_add_u32 s6, s35, s6
	s_addc_u32 s7, s39, s7
	s_lshl_b32 s8, s38, 2
	s_add_u32 s16, s42, s8
	s_waitcnt vmcnt(6)
	v_lshlrev_b32_e32 v64, 2, v193
	s_addc_u32 s17, s43, 0
	v_ashrrev_i32_e32 v65, 31, v64
	v_lshl_add_u64 v[64:65], v[64:65], 2, s[16:17]
	s_waitcnt vmcnt(3)
	v_lshlrev_b32_e32 v81, 2, v192
	global_load_dwordx4 v[76:79], v[64:65], off
	global_load_dwordx4 v[72:75], v[64:65], off offset:32
	global_load_dwordx4 v[68:71], v[64:65], off offset:64
	s_nop 0
	global_load_dwordx4 v[64:67], v[64:65], off offset:96
	v_lshlrev_b32_e32 v80, 11, v193
	global_load_dword v82, v81, s[24:25]
	global_load_dword v246, v81, s[24:25] offset:128
	global_load_dword v247, v81, s[24:25] offset:256
	global_load_dword v243, v81, s[24:25] offset:384
	v_add3_u32 v80, s33, v80, v81
	v_add_u32_e32 v144, s38, v147
	s_waitcnt vmcnt(0)
	v_fma_f32 v48, v48, v82, v76
	v_fma_f32 v49, v49, v82, v77
	v_fma_f32 v50, v50, v82, v78
	v_fma_f32 v51, v51, v82, v79
	v_fma_f32 v52, v52, v82, v72
	v_fma_f32 v53, v53, v82, v73
	v_fma_f32 v54, v54, v82, v74
	v_fma_f32 v55, v55, v82, v75
	v_fma_f32 v56, v56, v82, v68
	v_fma_f32 v57, v57, v82, v69
	v_fma_f32 v58, v58, v82, v70
	v_fma_f32 v59, v59, v82, v71
	v_fma_f32 v60, v60, v82, v64
	v_fma_f32 v61, v61, v82, v65
	v_fma_f32 v62, v62, v82, v66
	v_fma_f32 v63, v63, v82, v67
	v_mov_b32_e32 v82, v246
	s_waitcnt vmcnt(0)
	v_fma_f32 v32, v32, v82, v76
	ds_write2_b32 v80, v48, v32 offset1:32
	v_fma_f32 v32, v33, v82, v77
	ds_write2_b32 v80, v49, v32 offset0:128 offset1:160
	v_fma_f32 v32, v34, v82, v78
	v_add_u32_e32 v33, 0x400, v80
	ds_write2_b32 v33, v50, v32 offset1:32
	v_fma_f32 v32, v35, v82, v79
	ds_write2_b32 v33, v51, v32 offset0:128 offset1:160
	v_fma_f32 v32, v36, v82, v72
	v_add_u32_e32 v34, 0x1000, v80
	ds_write2_b32 v34, v52, v32 offset1:32
	v_fma_f32 v32, v37, v82, v73
	ds_write2_b32 v34, v53, v32 offset0:128 offset1:160
	v_fma_f32 v32, v38, v82, v74
	v_add_u32_e32 v35, 0x1400, v80
	ds_write2_b32 v35, v54, v32 offset1:32
	v_fma_f32 v32, v39, v82, v75
	ds_write2_b32 v35, v55, v32 offset0:128 offset1:160
	v_fma_f32 v32, v40, v82, v68
	v_add_u32_e32 v36, 0x2000, v80
	ds_write2_b32 v36, v56, v32 offset1:32
	v_fma_f32 v32, v41, v82, v69
	ds_write2_b32 v36, v57, v32 offset0:128 offset1:160
	v_fma_f32 v32, v42, v82, v70
	v_add_u32_e32 v37, 0x2400, v80
	ds_write2_b32 v37, v58, v32 offset1:32
	v_fma_f32 v32, v43, v82, v71
	ds_write2_b32 v37, v59, v32 offset0:128 offset1:160
	v_fma_f32 v32, v44, v82, v64
	v_add_u32_e32 v38, 0x3000, v80
	ds_write2_b32 v38, v60, v32 offset1:32
	v_fma_f32 v32, v45, v82, v65
	ds_write2_b32 v38, v61, v32 offset0:128 offset1:160
	v_fma_f32 v32, v46, v82, v66
	v_add_u32_e32 v39, 0x3400, v80
	ds_write2_b32 v39, v62, v32 offset1:32
	v_fma_f32 v32, v47, v82, v67
	ds_write2_b32 v39, v63, v32 offset0:128 offset1:160
	v_mov_b32_e32 v32, v247
	s_waitcnt vmcnt(0)
	v_fma_f32 v16, v16, v32, v76
	v_fma_f32 v17, v17, v32, v77
	v_fma_f32 v18, v18, v32, v78
	v_fma_f32 v19, v19, v32, v79
	v_fma_f32 v20, v20, v32, v72
	v_fma_f32 v21, v21, v32, v73
	v_fma_f32 v22, v22, v32, v74
	v_fma_f32 v23, v23, v32, v75
	v_fma_f32 v24, v24, v32, v68
	v_fma_f32 v25, v25, v32, v69
	v_fma_f32 v26, v26, v32, v70
	v_fma_f32 v27, v27, v32, v71
	v_fma_f32 v28, v28, v32, v64
	v_fma_f32 v29, v29, v32, v65
	v_fma_f32 v30, v30, v32, v66
	v_fma_f32 v31, v31, v32, v67
	v_mov_b32_e32 v32, v243
	s_waitcnt vmcnt(0)
	v_fma_f32 v0, v0, v32, v76
	ds_write2_b32 v80, v16, v0 offset0:64 offset1:96
	v_fma_f32 v0, v1, v32, v77
	ds_write2_b32 v80, v17, v0 offset0:192 offset1:224
	v_fma_f32 v0, v2, v32, v78
	ds_write2_b32 v33, v18, v0 offset0:64 offset1:96
	v_fma_f32 v0, v4, v32, v72
	ds_write2_b32 v34, v20, v0 offset0:64 offset1:96
	v_fma_f32 v0, v5, v32, v73
	ds_write2_b32 v34, v21, v0 offset0:192 offset1:224
	v_fma_f32 v0, v6, v32, v74
	ds_write2_b32 v35, v22, v0 offset0:64 offset1:96
	v_fma_f32 v0, v8, v32, v68
	ds_write2_b32 v36, v24, v0 offset0:64 offset1:96
	v_fma_f32 v0, v9, v32, v69
	ds_write2_b32 v36, v25, v0 offset0:192 offset1:224
	v_fma_f32 v0, v10, v32, v70
	ds_write2_b32 v37, v26, v0 offset0:64 offset1:96
	v_fma_f32 v0, v12, v32, v64
	ds_write2_b32 v38, v28, v0 offset0:64 offset1:96
	v_fma_f32 v0, v13, v32, v65
	ds_write2_b32 v38, v29, v0 offset0:192 offset1:224
	v_fma_f32 v0, v14, v32, v66
	ds_write2_b32 v39, v30, v0 offset0:64 offset1:96
	v_lshl_add_u64 v[0:1], s[2:3], 0, v[158:159]
	v_fmac_f32_e32 v79, v3, v32
	v_mad_i64_i32 v[2:3], s[2:3], v148, s69, v[0:1]
	v_fmac_f32_e32 v71, v11, v32
	global_load_dwordx4 v[8:11], v[2:3], off
	v_add_u32_e32 v96, s38, v205
	v_mad_i64_i32 v[98:99], s[2:3], v96, s69, v[0:1]
	global_load_dwordx4 v[100:103], v[98:99], off
	v_add_u32_e32 v96, s38, v202
	v_mad_i64_i32 v[98:99], s[2:3], v96, s69, v[0:1]
	global_load_dwordx4 v[104:107], v[98:99], off
	v_add_u32_e32 v96, s38, v201
	v_mad_i64_i32 v[98:99], s[2:3], v96, s69, v[0:1]
	global_load_dwordx4 v[108:111], v[98:99], off
	v_add_u32_e32 v96, s38, v200
	v_mad_i64_i32 v[98:99], s[2:3], v96, s69, v[0:1]
	global_load_dwordx4 v[112:115], v[98:99], off
	v_add_u32_e32 v96, s38, v199
	v_mad_i64_i32 v[98:99], s[2:3], v96, s69, v[0:1]
	global_load_dwordx4 v[116:119], v[98:99], off
	v_add_u32_e32 v96, s38, v145
	v_mad_i64_i32 v[98:99], s[2:3], v96, s69, v[0:1]
	global_load_dwordx4 v[120:123], v[98:99], off
	v_mad_i64_i32 v[98:99], s[2:3], v144, s69, v[0:1]
	global_load_dwordx4 v[124:127], v[98:99], off
	v_fmac_f32_e32 v75, v7, v32
	v_fmac_f32_e32 v67, v15, v32
	v_lshl_add_u32 v6, v149, 5, s33
	ds_write2_b32 v33, v19, v79 offset0:192 offset1:224
	ds_write2_b32 v35, v23, v75 offset0:192 offset1:224
	ds_write2_b32 v37, v27, v71 offset0:192 offset1:224
	ds_write2_b32 v39, v31, v67 offset0:192 offset1:224
	v_lshl_add_u32 v2, v213, 9, v6
	ds_read_b128 v[12:15], v2
	ds_read_b128 v[16:19], v2 offset:16
	v_ashrrev_i32_e32 v149, 31, v148
	v_lshl_add_u64 v[4:5], s[6:7], 0, v[158:159]
	v_lshl_add_u32 v7, v205, 9, v6
	s_waitcnt vmcnt(7)
	v_lshlrev_b32_e32 v2, 16, v8
	v_and_b32_e32 v3, 0xffff0000, v8
	s_waitcnt lgkmcnt(1)
	v_pk_mul_f32 v[2:3], v[12:13], v[2:3]
	s_nop 0
	v_cvt_pk_bf16_f32 v8, v2, v3
	v_lshlrev_b32_e32 v2, 16, v9
	v_and_b32_e32 v3, 0xffff0000, v9
	v_pk_mul_f32 v[2:3], v[14:15], v[2:3]
	s_nop 0
	v_cvt_pk_bf16_f32 v9, v2, v3
	v_lshlrev_b32_e32 v2, 16, v10
	v_and_b32_e32 v3, 0xffff0000, v10
	s_waitcnt lgkmcnt(0)
	v_pk_mul_f32 v[2:3], v[16:17], v[2:3]
	s_nop 0
	v_cvt_pk_bf16_f32 v10, v2, v3
	v_lshlrev_b32_e32 v2, 16, v11
	v_and_b32_e32 v3, 0xffff0000, v11
	v_pk_mul_f32 v[2:3], v[18:19], v[2:3]
	s_nop 0
	v_cvt_pk_bf16_f32 v11, v2, v3
	v_lshlrev_b64 v[2:3], 11, v[148:149]
	v_lshl_add_u64 v[2:3], v[4:5], 0, v[2:3]
	global_store_dwordx4 v[2:3], v[8:11], off sc1
	v_add_u32_e32 v2, s38, v205
	v_ashrrev_i32_e32 v3, 31, v2
	ds_read_b128 v[12:15], v7
	ds_read_b128 v[16:19], v7 offset:16
	v_lshlrev_b64 v[2:3], 11, v[2:3]
	v_lshl_add_u64 v[2:3], v[4:5], 0, v[2:3]
	v_lshl_add_u32 v7, v202, 9, v6
	s_waitcnt vmcnt(7)
	v_mov_b32_e32 v8, v100
	v_mov_b32_e32 v9, v101
	v_mov_b32_e32 v10, v102
	v_mov_b32_e32 v11, v103
	v_lshlrev_b32_e32 v20, 16, v8
	v_and_b32_e32 v21, 0xffff0000, v8
	s_waitcnt lgkmcnt(1)
	v_pk_mul_f32 v[12:13], v[12:13], v[20:21]
	s_nop 0
	v_cvt_pk_bf16_f32 v8, v12, v13
	v_lshlrev_b32_e32 v12, 16, v9
	v_and_b32_e32 v13, 0xffff0000, v9
	v_pk_mul_f32 v[12:13], v[14:15], v[12:13]
	s_nop 0
	v_cvt_pk_bf16_f32 v9, v12, v13
	v_lshlrev_b32_e32 v12, 16, v10
	v_and_b32_e32 v13, 0xffff0000, v10
	s_waitcnt lgkmcnt(0)
	v_pk_mul_f32 v[12:13], v[16:17], v[12:13]
	s_nop 0
	v_cvt_pk_bf16_f32 v10, v12, v13
	v_lshlrev_b32_e32 v12, 16, v11
	v_and_b32_e32 v13, 0xffff0000, v11
	v_pk_mul_f32 v[12:13], v[18:19], v[12:13]
	s_nop 0
	v_cvt_pk_bf16_f32 v11, v12, v13
	global_store_dwordx4 v[2:3], v[8:11], off sc1
	v_add_u32_e32 v2, s38, v202
	v_ashrrev_i32_e32 v3, 31, v2
	ds_read_b128 v[12:15], v7
	ds_read_b128 v[16:19], v7 offset:16
	v_lshlrev_b64 v[2:3], 11, v[2:3]
	v_lshl_add_u64 v[2:3], v[4:5], 0, v[2:3]
	v_lshl_add_u32 v7, v201, 9, v6
	s_waitcnt vmcnt(7)
	v_mov_b32_e32 v8, v104
	v_mov_b32_e32 v9, v105
	v_mov_b32_e32 v10, v106
	v_mov_b32_e32 v11, v107
	v_lshlrev_b32_e32 v20, 16, v8
	v_and_b32_e32 v21, 0xffff0000, v8
	s_waitcnt lgkmcnt(1)
	v_pk_mul_f32 v[12:13], v[12:13], v[20:21]
	s_nop 0
	v_cvt_pk_bf16_f32 v8, v12, v13
	v_lshlrev_b32_e32 v12, 16, v9
	v_and_b32_e32 v13, 0xffff0000, v9
	v_pk_mul_f32 v[12:13], v[14:15], v[12:13]
	s_nop 0
	v_cvt_pk_bf16_f32 v9, v12, v13
	v_lshlrev_b32_e32 v12, 16, v10
	v_and_b32_e32 v13, 0xffff0000, v10
	s_waitcnt lgkmcnt(0)
	v_pk_mul_f32 v[12:13], v[16:17], v[12:13]
	s_nop 0
	v_cvt_pk_bf16_f32 v10, v12, v13
	v_lshlrev_b32_e32 v12, 16, v11
	v_and_b32_e32 v13, 0xffff0000, v11
	v_pk_mul_f32 v[12:13], v[18:19], v[12:13]
	s_nop 0
	v_cvt_pk_bf16_f32 v11, v12, v13
	global_store_dwordx4 v[2:3], v[8:11], off sc1
	v_add_u32_e32 v2, s38, v201
	v_ashrrev_i32_e32 v3, 31, v2
	ds_read_b128 v[12:15], v7
	ds_read_b128 v[16:19], v7 offset:16
	v_lshlrev_b64 v[2:3], 11, v[2:3]
	v_lshl_add_u64 v[2:3], v[4:5], 0, v[2:3]
	v_lshl_add_u32 v7, v200, 9, v6
	s_waitcnt vmcnt(7)
	v_mov_b32_e32 v8, v108
	v_mov_b32_e32 v9, v109
	v_mov_b32_e32 v10, v110
	v_mov_b32_e32 v11, v111
	v_lshlrev_b32_e32 v20, 16, v8
	v_and_b32_e32 v21, 0xffff0000, v8
	s_waitcnt lgkmcnt(1)
	v_pk_mul_f32 v[12:13], v[12:13], v[20:21]
	s_nop 0
	v_cvt_pk_bf16_f32 v8, v12, v13
	v_lshlrev_b32_e32 v12, 16, v9
	v_and_b32_e32 v13, 0xffff0000, v9
	v_pk_mul_f32 v[12:13], v[14:15], v[12:13]
	s_nop 0
	v_cvt_pk_bf16_f32 v9, v12, v13
	v_lshlrev_b32_e32 v12, 16, v10
	v_and_b32_e32 v13, 0xffff0000, v10
	s_waitcnt lgkmcnt(0)
	v_pk_mul_f32 v[12:13], v[16:17], v[12:13]
	s_nop 0
	v_cvt_pk_bf16_f32 v10, v12, v13
	v_lshlrev_b32_e32 v12, 16, v11
	v_and_b32_e32 v13, 0xffff0000, v11
	v_pk_mul_f32 v[12:13], v[18:19], v[12:13]
	s_nop 0
	v_cvt_pk_bf16_f32 v11, v12, v13
	global_store_dwordx4 v[2:3], v[8:11], off sc1
	v_add_u32_e32 v2, s38, v200
	v_ashrrev_i32_e32 v3, 31, v2
	ds_read_b128 v[12:15], v7
	ds_read_b128 v[16:19], v7 offset:16
	v_lshlrev_b64 v[2:3], 11, v[2:3]
	v_lshl_add_u64 v[2:3], v[4:5], 0, v[2:3]
	v_lshl_add_u32 v7, v199, 9, v6
	s_waitcnt vmcnt(7)
	v_mov_b32_e32 v8, v112
	v_mov_b32_e32 v9, v113
	v_mov_b32_e32 v10, v114
	v_mov_b32_e32 v11, v115
	v_lshlrev_b32_e32 v20, 16, v8
	v_and_b32_e32 v21, 0xffff0000, v8
	s_waitcnt lgkmcnt(1)
	v_pk_mul_f32 v[12:13], v[12:13], v[20:21]
	s_nop 0
	v_cvt_pk_bf16_f32 v8, v12, v13
	v_lshlrev_b32_e32 v12, 16, v9
	v_and_b32_e32 v13, 0xffff0000, v9
	v_pk_mul_f32 v[12:13], v[14:15], v[12:13]
	s_nop 0
	v_cvt_pk_bf16_f32 v9, v12, v13
	v_lshlrev_b32_e32 v12, 16, v10
	v_and_b32_e32 v13, 0xffff0000, v10
	s_waitcnt lgkmcnt(0)
	v_pk_mul_f32 v[12:13], v[16:17], v[12:13]
	s_nop 0
	v_cvt_pk_bf16_f32 v10, v12, v13
	v_lshlrev_b32_e32 v12, 16, v11
	v_and_b32_e32 v13, 0xffff0000, v11
	v_pk_mul_f32 v[12:13], v[18:19], v[12:13]
	s_nop 0
	v_cvt_pk_bf16_f32 v11, v12, v13
	global_store_dwordx4 v[2:3], v[8:11], off sc1
	v_add_u32_e32 v2, s38, v199
	v_ashrrev_i32_e32 v3, 31, v2
	ds_read_b128 v[12:15], v7
	ds_read_b128 v[16:19], v7 offset:16
	v_lshlrev_b64 v[2:3], 11, v[2:3]
	v_lshl_add_u64 v[2:3], v[4:5], 0, v[2:3]
	v_lshl_add_u32 v7, v145, 9, v6
	s_waitcnt vmcnt(7)
	v_mov_b32_e32 v8, v116
	v_mov_b32_e32 v9, v117
	v_mov_b32_e32 v10, v118
	v_mov_b32_e32 v11, v119
	v_lshlrev_b32_e32 v20, 16, v8
	v_and_b32_e32 v21, 0xffff0000, v8
	s_waitcnt lgkmcnt(1)
	v_pk_mul_f32 v[12:13], v[12:13], v[20:21]
	s_nop 0
	v_cvt_pk_bf16_f32 v8, v12, v13
	v_lshlrev_b32_e32 v12, 16, v9
	v_and_b32_e32 v13, 0xffff0000, v9
	v_pk_mul_f32 v[12:13], v[14:15], v[12:13]
	s_nop 0
	v_cvt_pk_bf16_f32 v9, v12, v13
	v_lshlrev_b32_e32 v12, 16, v10
	v_and_b32_e32 v13, 0xffff0000, v10
	s_waitcnt lgkmcnt(0)
	v_pk_mul_f32 v[12:13], v[16:17], v[12:13]
	s_nop 0
	v_cvt_pk_bf16_f32 v10, v12, v13
	v_lshlrev_b32_e32 v12, 16, v11
	v_and_b32_e32 v13, 0xffff0000, v11
	v_pk_mul_f32 v[12:13], v[18:19], v[12:13]
	s_nop 0
	v_cvt_pk_bf16_f32 v11, v12, v13
	global_store_dwordx4 v[2:3], v[8:11], off sc1
	v_add_u32_e32 v2, s38, v145
	v_ashrrev_i32_e32 v3, 31, v2
	ds_read_b128 v[12:15], v7
	ds_read_b128 v[16:19], v7 offset:16
	v_lshlrev_b64 v[2:3], 11, v[2:3]
	v_lshl_add_u64 v[2:3], v[4:5], 0, v[2:3]
	v_ashrrev_i32_e32 v145, 31, v144
	s_waitcnt vmcnt(7)
	v_mov_b32_e32 v8, v120
	v_mov_b32_e32 v9, v121
	v_mov_b32_e32 v10, v122
	v_mov_b32_e32 v11, v123
	v_lshlrev_b32_e32 v20, 16, v8
	v_and_b32_e32 v21, 0xffff0000, v8
	s_waitcnt lgkmcnt(1)
	v_pk_mul_f32 v[12:13], v[12:13], v[20:21]
	s_nop 0
	v_cvt_pk_bf16_f32 v8, v12, v13
	v_lshlrev_b32_e32 v12, 16, v9
	v_and_b32_e32 v13, 0xffff0000, v9
	v_pk_mul_f32 v[12:13], v[14:15], v[12:13]
	s_nop 0
	v_cvt_pk_bf16_f32 v9, v12, v13
	v_lshlrev_b32_e32 v12, 16, v10
	v_and_b32_e32 v13, 0xffff0000, v10
	s_waitcnt lgkmcnt(0)
	v_pk_mul_f32 v[12:13], v[16:17], v[12:13]
	s_nop 0
	v_cvt_pk_bf16_f32 v10, v12, v13
	v_lshlrev_b32_e32 v12, 16, v11
	v_and_b32_e32 v13, 0xffff0000, v11
	v_pk_mul_f32 v[12:13], v[18:19], v[12:13]
	s_nop 0
	v_cvt_pk_bf16_f32 v11, v12, v13
	global_store_dwordx4 v[2:3], v[8:11], off sc1
	s_waitcnt vmcnt(7)
	v_mov_b32_e32 v0, v124
	v_mov_b32_e32 v1, v125
	v_mov_b32_e32 v2, v126
	v_mov_b32_e32 v3, v127
	v_lshlrev_b32_e32 v14, 16, v0
	v_lshl_add_u32 v10, v147, 9, v6
	ds_read_b128 v[6:9], v10
	ds_read_b128 v[10:13], v10 offset:16
	v_and_b32_e32 v15, 0xffff0000, v0
	s_waitcnt lgkmcnt(1)
	v_pk_mul_f32 v[6:7], v[6:7], v[14:15]
	s_nop 0
	v_cvt_pk_bf16_f32 v0, v6, v7
	v_lshlrev_b32_e32 v6, 16, v1
	v_and_b32_e32 v7, 0xffff0000, v1
	v_pk_mul_f32 v[6:7], v[8:9], v[6:7]
	s_nop 0
	v_cvt_pk_bf16_f32 v1, v6, v7
	v_lshlrev_b32_e32 v6, 16, v2
	v_and_b32_e32 v7, 0xffff0000, v2
	s_waitcnt lgkmcnt(0)
	v_pk_mul_f32 v[6:7], v[10:11], v[6:7]
	s_nop 0
	v_cvt_pk_bf16_f32 v2, v6, v7
	v_lshlrev_b32_e32 v6, 16, v3
	v_and_b32_e32 v7, 0xffff0000, v3
	v_pk_mul_f32 v[6:7], v[12:13], v[6:7]
	s_nop 0
	v_cvt_pk_bf16_f32 v3, v6, v7

.LBB0_254:
	s_ashr_i32 s41, s40, 31
	s_lshl_b64 s[42:43], s[40:41], 19
	s_add_u32 s42, s30, s42
	s_addc_u32 s43, s31, s43
	s_and_b64 s[44:45], s[38:39], exec
	s_cselect_b32 s41, s43, s47
	s_cselect_b32 s96, s42, s46
	s_ashr_i32 s35, s34, 31
	s_lshl_b64 s[44:45], s[34:35], 19
	s_add_u32 s44, s8, s44
	s_addc_u32 s45, s81, s45
	s_and_b64 s[50:51], s[38:39], exec
	s_cselect_b32 s35, s45, s49
	s_cselect_b32 s97, s44, s48
	s_add_u32 s46, s46, 0x40080
	s_addc_u32 s47, s47, 0
	s_add_u32 vcc_lo, s48, 0x100
	s_addc_u32 vcc_hi, s49, 0
	s_mov_b32 s60, -2
	s_add_u32 s48, s46, 0xfffc0080
	s_addc_u32 s49, s47, -1
	s_add_i32 s62, 0, 0x10000
	s_cmp_eq_u32 s60, 12
	s_cselect_b32 s51, s41, s49
	s_cselect_b32 s50, s96, s48
	v_add_u32_e32 v138, s62, v142
	s_cselect_b32 s49, s35, vcc_hi
	s_cselect_b32 s48, s97, vcc_lo
	s_add_i32 s61, 0, 0x14000
	ds_read_b128 v[144:147], v138
	ds_read_b128 v[148:151], v138 offset:1024
	ds_read_b128 v[152:155], v138 offset:2048
	ds_read_b128 v[168:171], v138 offset:3072
	v_add_u32_e32 v138, s61, v142
	ds_read_b128 v[172:175], v138
	ds_read_b128 v[176:179], v138 offset:1024
	ds_read_b128 v[180:183], v138 offset:2048
	ds_read_b128 v[184:187], v138 offset:3072
	v_lshl_add_u64 v[138:139], s[46:47], 0, v[134:135]
	s_add_i32 m0, s65, 0xc000
	ds_read_b128 v[188:191], v143
	ds_read_b128 v[200:203], v143 offset:1024
	ds_read_b128 v[204:207], v143 offset:2048
	ds_read_b128 v[208:211], v143 offset:3072
	ds_read_b128 v[212:215], v143 offset:4096
	ds_read_b128 v[216:219], v143 offset:5120
	ds_read_b128 v[220:223], v143 offset:6144
	ds_read_b128 v[224:227], v143 offset:7168
	global_load_lds_dwordx4 v[138:139], off
	v_lshl_add_u64 v[138:139], s[46:47], 0, v[136:137]
	s_add_i32 m0, s65, 0xe000
	s_nop 0
	global_load_lds_dwordx4 v[138:139], off
	s_waitcnt vmcnt(8)
	s_waitcnt lgkmcnt(0)
	s_barrier
	s_setprio 1
	v_mfma_f32_16x16x32_bf16 v[124:127], v[144:147], v[188:191], 0
	v_mfma_f32_16x16x32_bf16 v[120:123], v[152:155], v[188:191], 0
	v_mfma_f32_16x16x32_bf16 v[108:111], v[144:147], v[204:207], 0
	v_mfma_f32_16x16x32_bf16 v[104:107], v[152:155], v[204:207], 0
	v_mfma_f32_16x16x32_bf16 v[92:95], v[144:147], v[212:215], 0
	v_mfma_f32_16x16x32_bf16 v[88:91], v[152:155], v[212:215], 0
	v_mfma_f32_16x16x32_bf16 v[76:79], v[144:147], v[220:223], 0
	v_mfma_f32_16x16x32_bf16 v[72:75], v[152:155], v[220:223], 0
	v_mfma_f32_16x16x32_bf16 v[124:127], v[148:151], v[200:203], v[124:127]
	v_mfma_f32_16x16x32_bf16 v[120:123], v[168:171], v[200:203], v[120:123]
	v_mfma_f32_16x16x32_bf16 v[108:111], v[148:151], v[208:211], v[108:111]
	v_mfma_f32_16x16x32_bf16 v[104:107], v[168:171], v[208:211], v[104:107]
	v_mfma_f32_16x16x32_bf16 v[92:95], v[148:151], v[216:219], v[92:95]
	v_mfma_f32_16x16x32_bf16 v[88:91], v[168:171], v[216:219], v[88:91]
	v_mfma_f32_16x16x32_bf16 v[76:79], v[148:151], v[224:227], v[76:79]
	v_mfma_f32_16x16x32_bf16 v[72:75], v[168:171], v[224:227], v[72:75]
	s_setprio 0
	s_setprio 1
	v_mfma_f32_16x16x32_bf16 v[116:119], v[172:175], v[188:191], 0
	v_mfma_f32_16x16x32_bf16 v[112:115], v[180:183], v[188:191], 0
	v_mfma_f32_16x16x32_bf16 v[100:103], v[172:175], v[204:207], 0
	v_mfma_f32_16x16x32_bf16 v[96:99], v[180:183], v[204:207], 0
	v_mfma_f32_16x16x32_bf16 v[84:87], v[172:175], v[212:215], 0
	v_mfma_f32_16x16x32_bf16 v[80:83], v[180:183], v[212:215], 0
	v_mfma_f32_16x16x32_bf16 v[68:71], v[172:175], v[220:223], 0
	v_mfma_f32_16x16x32_bf16 v[64:67], v[180:183], v[220:223], 0
	v_mfma_f32_16x16x32_bf16 v[116:119], v[176:179], v[200:203], v[116:119]
	v_mfma_f32_16x16x32_bf16 v[112:115], v[184:187], v[200:203], v[112:115]
	v_mfma_f32_16x16x32_bf16 v[100:103], v[176:179], v[208:211], v[100:103]
	v_mfma_f32_16x16x32_bf16 v[96:99], v[184:187], v[208:211], v[96:99]
	v_mfma_f32_16x16x32_bf16 v[84:87], v[176:179], v[216:219], v[84:87]
	v_mfma_f32_16x16x32_bf16 v[80:83], v[184:187], v[216:219], v[80:83]
	v_mfma_f32_16x16x32_bf16 v[68:71], v[176:179], v[224:227], v[68:71]
	v_mfma_f32_16x16x32_bf16 v[64:67], v[184:187], v[224:227], v[64:67]
	s_setprio 0
	s_barrier
	s_add_i32 s62, s62, s64
	v_lshl_add_u64 v[138:139], s[48:49], 0, v[158:159]
	s_mov_b32 m0, s62
	ds_read_b128 v[188:191], v143 offset:16384
	ds_read_b128 v[200:203], v143 offset:17408
	ds_read_b128 v[204:207], v143 offset:18432
	ds_read_b128 v[208:211], v143 offset:19456
	ds_read_b128 v[212:215], v143 offset:20480
	ds_read_b128 v[216:219], v143 offset:21504
	ds_read_b128 v[220:223], v143 offset:22528
	ds_read_b128 v[224:227], v143 offset:23552
	global_load_lds_dwordx4 v[138:139], off
	s_add_i32 m0, s62, 0x2000
	s_add_u32 s62, s48, 0x40000
	v_lshl_add_u64 v[192:193], s[48:49], 0, v[128:129]
	s_addc_u32 s63, s49, 0
	s_add_i32 s61, s61, s64
	global_load_lds_dwordx4 v[192:193], off
	v_lshl_add_u64 v[228:229], s[62:63], 0, v[158:159]
	s_mov_b32 m0, s61
	v_lshl_add_u64 v[230:231], s[50:51], 0, v[130:131]
	global_load_lds_dwordx4 v[228:229], off
	v_lshl_add_u64 v[228:229], s[62:63], 0, v[128:129]
	s_add_i32 m0, s61, 0x2000
	s_nop 0
	global_load_lds_dwordx4 v[228:229], off
	v_lshl_add_u64 v[228:229], s[50:51], 0, v[132:133]
	s_mov_b32 m0, s65
	s_nop 0
	global_load_lds_dwordx4 v[228:229], off
	s_mov_b32 m0, s82
	s_nop 0
	global_load_lds_dwordx4 v[230:231], off
	s_waitcnt vmcnt(8)
	s_waitcnt lgkmcnt(0)
	s_barrier
	s_setprio 1
	v_mfma_f32_16x16x32_bf16 v[60:63], v[144:147], v[188:191], 0
	v_mfma_f32_16x16x32_bf16 v[56:59], v[152:155], v[188:191], 0
	v_mfma_f32_16x16x32_bf16 v[44:47], v[144:147], v[204:207], 0
	v_mfma_f32_16x16x32_bf16 v[40:43], v[152:155], v[204:207], 0
	v_mfma_f32_16x16x32_bf16 v[28:31], v[144:147], v[212:215], 0
	v_mfma_f32_16x16x32_bf16 v[24:27], v[152:155], v[212:215], 0
	v_mfma_f32_16x16x32_bf16 v[12:15], v[144:147], v[220:223], 0
	v_mfma_f32_16x16x32_bf16 v[8:11], v[152:155], v[220:223], 0
	v_mfma_f32_16x16x32_bf16 v[60:63], v[148:151], v[200:203], v[60:63]
	v_mfma_f32_16x16x32_bf16 v[56:59], v[168:171], v[200:203], v[56:59]
	v_mfma_f32_16x16x32_bf16 v[44:47], v[148:151], v[208:211], v[44:47]
	v_mfma_f32_16x16x32_bf16 v[40:43], v[168:171], v[208:211], v[40:43]
	v_mfma_f32_16x16x32_bf16 v[28:31], v[148:151], v[216:219], v[28:31]
	v_mfma_f32_16x16x32_bf16 v[24:27], v[168:171], v[216:219], v[24:27]
	v_mfma_f32_16x16x32_bf16 v[12:15], v[148:151], v[224:227], v[12:15]
	v_mfma_f32_16x16x32_bf16 v[8:11], v[168:171], v[224:227], v[8:11]
	s_setprio 0
	s_setprio 1
	v_mfma_f32_16x16x32_bf16 v[52:55], v[172:175], v[188:191], 0
	v_mfma_f32_16x16x32_bf16 v[48:51], v[180:183], v[188:191], 0
	v_mfma_f32_16x16x32_bf16 v[36:39], v[172:175], v[204:207], 0
	v_mfma_f32_16x16x32_bf16 v[32:35], v[180:183], v[204:207], 0
	v_mfma_f32_16x16x32_bf16 v[20:23], v[172:175], v[212:215], 0
	v_mfma_f32_16x16x32_bf16 v[16:19], v[180:183], v[212:215], 0
	v_mfma_f32_16x16x32_bf16 v[4:7], v[172:175], v[220:223], 0
	v_mfma_f32_16x16x32_bf16 v[0:3], v[180:183], v[220:223], 0
	v_mfma_f32_16x16x32_bf16 v[52:55], v[176:179], v[200:203], v[52:55]
	v_mfma_f32_16x16x32_bf16 v[48:51], v[184:187], v[200:203], v[48:51]
	v_mfma_f32_16x16x32_bf16 v[36:39], v[176:179], v[208:211], v[36:39]
	v_mfma_f32_16x16x32_bf16 v[32:35], v[184:187], v[208:211], v[32:35]
	v_mfma_f32_16x16x32_bf16 v[20:23], v[176:179], v[216:219], v[20:23]
	v_mfma_f32_16x16x32_bf16 v[16:19], v[184:187], v[216:219], v[16:19]
	v_mfma_f32_16x16x32_bf16 v[4:7], v[176:179], v[224:227], v[4:7]
	v_mfma_f32_16x16x32_bf16 v[0:3], v[184:187], v[224:227], v[0:3]
	s_setprio 0
	s_barrier
	s_add_i32 s61, 0, 0x18000
	s_add_i32 s62, 0, 0x1c000
	v_add_u32_e32 v168, s61, v142
	v_add_u32_e32 v184, s62, v142
	ds_read_b128 v[144:147], v168
	ds_read_b128 v[148:151], v168 offset:1024
	ds_read_b128 v[152:155], v168 offset:2048
	ds_read_b128 v[168:171], v168 offset:3072
	ds_read_b128 v[172:175], v184
	ds_read_b128 v[176:179], v184 offset:1024
	ds_read_b128 v[180:183], v184 offset:2048
	ds_read_b128 v[184:187], v184 offset:3072
	s_add_u32 s50, s50, 0x40000
	s_addc_u32 s51, s51, 0
	s_mov_b32 m0, s83
	v_lshl_add_u64 v[232:233], s[50:51], 0, v[132:133]
	ds_read_b128 v[188:191], v143 offset:32768
	ds_read_b128 v[200:203], v143 offset:33792
	ds_read_b128 v[204:207], v143 offset:34816
	ds_read_b128 v[208:211], v143 offset:35840
	ds_read_b128 v[212:215], v143 offset:36864
	ds_read_b128 v[216:219], v143 offset:37888
	ds_read_b128 v[220:223], v143 offset:38912
	ds_read_b128 v[224:227], v143 offset:39936
	global_load_lds_dwordx4 v[232:233], off
	v_lshl_add_u64 v[232:233], s[50:51], 0, v[130:131]
	s_mov_b32 m0, s84
	s_nop 0
	global_load_lds_dwordx4 v[232:233], off
	s_waitcnt vmcnt(8)
	s_waitcnt lgkmcnt(0)
	s_barrier
	s_setprio 1
	v_mfma_f32_16x16x32_bf16 v[124:127], v[144:147], v[188:191], v[124:127]
	v_mfma_f32_16x16x32_bf16 v[120:123], v[152:155], v[188:191], v[120:123]
	v_mfma_f32_16x16x32_bf16 v[108:111], v[144:147], v[204:207], v[108:111]
	v_mfma_f32_16x16x32_bf16 v[104:107], v[152:155], v[204:207], v[104:107]
	v_mfma_f32_16x16x32_bf16 v[92:95], v[144:147], v[212:215], v[92:95]
	v_mfma_f32_16x16x32_bf16 v[88:91], v[152:155], v[212:215], v[88:91]
	v_mfma_f32_16x16x32_bf16 v[76:79], v[144:147], v[220:223], v[76:79]
	v_mfma_f32_16x16x32_bf16 v[72:75], v[152:155], v[220:223], v[72:75]
	v_mfma_f32_16x16x32_bf16 v[124:127], v[148:151], v[200:203], v[124:127]
	v_mfma_f32_16x16x32_bf16 v[120:123], v[168:171], v[200:203], v[120:123]
	v_mfma_f32_16x16x32_bf16 v[108:111], v[148:151], v[208:211], v[108:111]
	v_mfma_f32_16x16x32_bf16 v[104:107], v[168:171], v[208:211], v[104:107]
	v_mfma_f32_16x16x32_bf16 v[92:95], v[148:151], v[216:219], v[92:95]
	v_mfma_f32_16x16x32_bf16 v[88:91], v[168:171], v[216:219], v[88:91]
	v_mfma_f32_16x16x32_bf16 v[76:79], v[148:151], v[224:227], v[76:79]
	v_mfma_f32_16x16x32_bf16 v[72:75], v[168:171], v[224:227], v[72:75]
	s_setprio 0
	s_setprio 1
	v_mfma_f32_16x16x32_bf16 v[116:119], v[172:175], v[188:191], v[116:119]
	v_mfma_f32_16x16x32_bf16 v[112:115], v[180:183], v[188:191], v[112:115]
	v_mfma_f32_16x16x32_bf16 v[100:103], v[172:175], v[204:207], v[100:103]
	v_mfma_f32_16x16x32_bf16 v[96:99], v[180:183], v[204:207], v[96:99]
	v_mfma_f32_16x16x32_bf16 v[84:87], v[172:175], v[212:215], v[84:87]
	v_mfma_f32_16x16x32_bf16 v[80:83], v[180:183], v[212:215], v[80:83]
	v_mfma_f32_16x16x32_bf16 v[68:71], v[172:175], v[220:223], v[68:71]
	v_mfma_f32_16x16x32_bf16 v[64:67], v[180:183], v[220:223], v[64:67]
	v_mfma_f32_16x16x32_bf16 v[116:119], v[176:179], v[200:203], v[116:119]
	v_mfma_f32_16x16x32_bf16 v[112:115], v[184:187], v[200:203], v[112:115]
	v_mfma_f32_16x16x32_bf16 v[100:103], v[176:179], v[208:211], v[100:103]
	v_mfma_f32_16x16x32_bf16 v[96:99], v[184:187], v[208:211], v[96:99]
	v_mfma_f32_16x16x32_bf16 v[84:87], v[176:179], v[216:219], v[84:87]
	v_mfma_f32_16x16x32_bf16 v[80:83], v[184:187], v[216:219], v[80:83]
	v_mfma_f32_16x16x32_bf16 v[68:71], v[176:179], v[224:227], v[68:71]
	v_mfma_f32_16x16x32_bf16 v[64:67], v[184:187], v[224:227], v[64:67]
	s_setprio 0
	s_barrier
	s_add_i32 s50, s61, s64
	v_lshl_add_u64 v[138:139], v[138:139], 0, s[14:15]
	s_mov_b32 m0, s50
	ds_read_b128 v[188:191], v143 offset:49152
	ds_read_b128 v[200:203], v143 offset:50176
	ds_read_b128 v[204:207], v143 offset:51200
	ds_read_b128 v[208:211], v143 offset:52224
	ds_read_b128 v[212:215], v143 offset:53248
	ds_read_b128 v[216:219], v143 offset:54272
	ds_read_b128 v[220:223], v143 offset:55296
	ds_read_b128 v[224:227], v143 offset:56320
	global_load_lds_dwordx4 v[138:139], off
	s_add_i32 m0, s50, 0x2000
	s_add_u32 s48, s48, 0x40080
	v_lshl_add_u64 v[138:139], v[192:193], 0, s[14:15]
	s_addc_u32 s49, s49, 0
	s_add_i32 s50, s62, s64
	global_load_lds_dwordx4 v[138:139], off
	v_lshl_add_u64 v[138:139], s[48:49], 0, v[158:159]
	s_mov_b32 m0, s50
	s_nop 0
	global_load_lds_dwordx4 v[138:139], off
	v_lshl_add_u64 v[138:139], s[48:49], 0, v[128:129]
	s_add_i32 m0, s50, 0x2000
	s_nop 0
	global_load_lds_dwordx4 v[138:139], off
	v_lshl_add_u64 v[138:139], v[228:229], 0, s[14:15]
	s_mov_b32 m0, s87
	s_nop 0
	global_load_lds_dwordx4 v[138:139], off
	v_lshl_add_u64 v[138:139], v[230:231], 0, s[14:15]
	s_mov_b32 m0, s88
	s_nop 0
	global_load_lds_dwordx4 v[138:139], off
	s_waitcnt vmcnt(8)
	s_waitcnt lgkmcnt(0)
	s_barrier
	s_setprio 1
	v_mfma_f32_16x16x32_bf16 v[60:63], v[144:147], v[188:191], v[60:63]
	v_mfma_f32_16x16x32_bf16 v[56:59], v[152:155], v[188:191], v[56:59]
	v_mfma_f32_16x16x32_bf16 v[44:47], v[144:147], v[204:207], v[44:47]
	v_mfma_f32_16x16x32_bf16 v[40:43], v[152:155], v[204:207], v[40:43]
	v_mfma_f32_16x16x32_bf16 v[28:31], v[144:147], v[212:215], v[28:31]
	v_mfma_f32_16x16x32_bf16 v[24:27], v[152:155], v[212:215], v[24:27]
	v_mfma_f32_16x16x32_bf16 v[12:15], v[144:147], v[220:223], v[12:15]
	v_mfma_f32_16x16x32_bf16 v[8:11], v[152:155], v[220:223], v[8:11]
	v_mfma_f32_16x16x32_bf16 v[60:63], v[148:151], v[200:203], v[60:63]
	v_mfma_f32_16x16x32_bf16 v[56:59], v[168:171], v[200:203], v[56:59]
	v_mfma_f32_16x16x32_bf16 v[44:47], v[148:151], v[208:211], v[44:47]
	v_mfma_f32_16x16x32_bf16 v[40:43], v[168:171], v[208:211], v[40:43]
	v_mfma_f32_16x16x32_bf16 v[28:31], v[148:151], v[216:219], v[28:31]
	v_mfma_f32_16x16x32_bf16 v[24:27], v[168:171], v[216:219], v[24:27]
	v_mfma_f32_16x16x32_bf16 v[12:15], v[148:151], v[224:227], v[12:15]
	v_mfma_f32_16x16x32_bf16 v[8:11], v[168:171], v[224:227], v[8:11]
	s_setprio 0
	s_setprio 1
	v_mfma_f32_16x16x32_bf16 v[52:55], v[172:175], v[188:191], v[52:55]
	v_mfma_f32_16x16x32_bf16 v[48:51], v[180:183], v[188:191], v[48:51]
	v_mfma_f32_16x16x32_bf16 v[36:39], v[172:175], v[204:207], v[36:39]
	v_mfma_f32_16x16x32_bf16 v[32:35], v[180:183], v[204:207], v[32:35]
	v_mfma_f32_16x16x32_bf16 v[20:23], v[172:175], v[212:215], v[20:23]
	v_mfma_f32_16x16x32_bf16 v[16:19], v[180:183], v[212:215], v[16:19]
	v_mfma_f32_16x16x32_bf16 v[4:7], v[172:175], v[220:223], v[4:7]
	v_mfma_f32_16x16x32_bf16 v[0:3], v[180:183], v[220:223], v[0:3]
	v_mfma_f32_16x16x32_bf16 v[52:55], v[176:179], v[200:203], v[52:55]
	v_mfma_f32_16x16x32_bf16 v[48:51], v[184:187], v[200:203], v[48:51]
	v_mfma_f32_16x16x32_bf16 v[36:39], v[176:179], v[208:211], v[36:39]
	v_mfma_f32_16x16x32_bf16 v[32:35], v[184:187], v[208:211], v[32:35]
	v_mfma_f32_16x16x32_bf16 v[20:23], v[176:179], v[216:219], v[20:23]
	v_mfma_f32_16x16x32_bf16 v[16:19], v[184:187], v[216:219], v[16:19]
	v_mfma_f32_16x16x32_bf16 v[4:7], v[176:179], v[224:227], v[4:7]
	v_mfma_f32_16x16x32_bf16 v[0:3], v[184:187], v[224:227], v[0:3]
	s_setprio 0
	s_barrier
	s_add_i32 s60, s60, 2
	s_add_u32 s46, s46, 0x100
	s_addc_u32 s47, s47, 0
	s_add_u32 vcc_lo, vcc_lo, 0x100
	s_addc_u32 vcc_hi, vcc_hi, 0

.LBB0_279:
	s_ashr_i32 s35, s34, 31
	s_lshl_b64 s[44:45], s[34:35], 19
	s_add_u32 s96, s30, s44
	s_addc_u32 s97, s31, s45
	s_and_b64 s[44:45], s[38:39], exec
	s_cselect_b32 s35, s97, s41
	s_cselect_b32 s48, s96, s40
	s_ashr_i32 s17, s16, 31
	s_lshl_b64 s[44:45], s[16:17], 19
	s_add_u32 s60, s8, s44
	s_addc_u32 s61, s81, s45
	s_and_b64 s[44:45], s[38:39], exec
	s_cselect_b32 s17, s61, s43
	s_cselect_b32 s49, s60, s42
	s_add_u32 s40, s40, 0x40080
	s_addc_u32 s41, s41, 0
	s_add_u32 s64, s42, 0x100
	s_addc_u32 s65, s43, 0
	s_mov_b32 vcc_lo, -2
	s_waitcnt lgkmcnt(0)
	s_add_u32 s42, s40, 0xfffc0080
	s_addc_u32 s43, s41, -1
	s_add_i32 s62, 0, 0x10000
	s_cmp_eq_u32 vcc_lo, 12
	s_cselect_b32 s45, s35, s43
	s_cselect_b32 s44, s48, s42
	v_add_u32_e32 v158, s62, v154
	s_cselect_b32 s43, s17, s65
	s_cselect_b32 s42, s49, s64
	s_add_i32 vcc_hi, 0, 0x14000
	ds_read_b128 v[140:143], v158
	ds_read_b128 v[144:147], v158 offset:1024
	ds_read_b128 v[148:151], v158 offset:2048
	ds_read_b128 v[168:171], v158 offset:3072
	v_add_u32_e32 v158, vcc_hi, v154
	ds_read_b128 v[172:175], v158
	ds_read_b128 v[176:179], v158 offset:1024
	ds_read_b128 v[180:183], v158 offset:2048
	ds_read_b128 v[184:187], v158 offset:3072
	v_lshl_add_u64 v[192:193], s[40:41], 0, v[136:137]
	s_add_i32 m0, s83, 0xc000
	ds_read_b128 v[188:191], v155
	ds_read_b128 v[200:203], v155 offset:1024
	ds_read_b128 v[204:207], v155 offset:2048
	ds_read_b128 v[208:211], v155 offset:3072
	ds_read_b128 v[212:215], v155 offset:4096
	ds_read_b128 v[216:219], v155 offset:5120
	ds_read_b128 v[220:223], v155 offset:6144
	ds_read_b128 v[224:227], v155 offset:7168
	global_load_lds_dwordx4 v[192:193], off
	v_lshl_add_u64 v[192:193], s[40:41], 0, v[138:139]
	s_add_i32 m0, s83, 0xe000
	s_nop 0
	global_load_lds_dwordx4 v[192:193], off
	s_waitcnt vmcnt(8)
	s_waitcnt lgkmcnt(0)
	s_barrier
	s_setprio 1
	v_mfma_f32_16x16x32_bf16 v[124:127], v[140:143], v[188:191], 0
	v_mfma_f32_16x16x32_bf16 v[120:123], v[148:151], v[188:191], 0
	v_mfma_f32_16x16x32_bf16 v[108:111], v[140:143], v[204:207], 0
	v_mfma_f32_16x16x32_bf16 v[104:107], v[148:151], v[204:207], 0
	v_mfma_f32_16x16x32_bf16 v[92:95], v[140:143], v[212:215], 0
	v_mfma_f32_16x16x32_bf16 v[88:91], v[148:151], v[212:215], 0
	v_mfma_f32_16x16x32_bf16 v[76:79], v[140:143], v[220:223], 0
	v_mfma_f32_16x16x32_bf16 v[72:75], v[148:151], v[220:223], 0
	v_mfma_f32_16x16x32_bf16 v[124:127], v[144:147], v[200:203], v[124:127]
	v_mfma_f32_16x16x32_bf16 v[120:123], v[168:171], v[200:203], v[120:123]
	v_mfma_f32_16x16x32_bf16 v[108:111], v[144:147], v[208:211], v[108:111]
	v_mfma_f32_16x16x32_bf16 v[104:107], v[168:171], v[208:211], v[104:107]
	v_mfma_f32_16x16x32_bf16 v[92:95], v[144:147], v[216:219], v[92:95]
	v_mfma_f32_16x16x32_bf16 v[88:91], v[168:171], v[216:219], v[88:91]
	v_mfma_f32_16x16x32_bf16 v[76:79], v[144:147], v[224:227], v[76:79]
	v_mfma_f32_16x16x32_bf16 v[72:75], v[168:171], v[224:227], v[72:75]
	s_setprio 0
	s_setprio 1
	v_mfma_f32_16x16x32_bf16 v[116:119], v[172:175], v[188:191], 0
	v_mfma_f32_16x16x32_bf16 v[112:115], v[180:183], v[188:191], 0
	v_mfma_f32_16x16x32_bf16 v[100:103], v[172:175], v[204:207], 0
	v_mfma_f32_16x16x32_bf16 v[96:99], v[180:183], v[204:207], 0
	v_mfma_f32_16x16x32_bf16 v[84:87], v[172:175], v[212:215], 0
	v_mfma_f32_16x16x32_bf16 v[80:83], v[180:183], v[212:215], 0
	v_mfma_f32_16x16x32_bf16 v[68:71], v[172:175], v[220:223], 0
	v_mfma_f32_16x16x32_bf16 v[64:67], v[180:183], v[220:223], 0
	v_mfma_f32_16x16x32_bf16 v[116:119], v[176:179], v[200:203], v[116:119]
	v_mfma_f32_16x16x32_bf16 v[112:115], v[184:187], v[200:203], v[112:115]
	v_mfma_f32_16x16x32_bf16 v[100:103], v[176:179], v[208:211], v[100:103]
	v_mfma_f32_16x16x32_bf16 v[96:99], v[184:187], v[208:211], v[96:99]
	v_mfma_f32_16x16x32_bf16 v[84:87], v[176:179], v[216:219], v[84:87]
	v_mfma_f32_16x16x32_bf16 v[80:83], v[184:187], v[216:219], v[80:83]
	v_mfma_f32_16x16x32_bf16 v[68:71], v[176:179], v[224:227], v[68:71]
	v_mfma_f32_16x16x32_bf16 v[64:67], v[184:187], v[224:227], v[64:67]
	s_setprio 0
	s_barrier
	s_add_i32 s62, s62, s82
	v_lshl_add_u64 v[192:193], s[42:43], 0, v[132:133]
	s_mov_b32 m0, s62
	ds_read_b128 v[188:191], v155 offset:16384
	ds_read_b128 v[200:203], v155 offset:17408
	ds_read_b128 v[204:207], v155 offset:18432
	ds_read_b128 v[208:211], v155 offset:19456
	ds_read_b128 v[212:215], v155 offset:20480
	ds_read_b128 v[216:219], v155 offset:21504
	ds_read_b128 v[220:223], v155 offset:22528
	ds_read_b128 v[224:227], v155 offset:23552
	global_load_lds_dwordx4 v[192:193], off
	s_add_i32 m0, s62, 0x2000
	s_add_u32 s62, s42, 0x40000
	v_lshl_add_u64 v[228:229], s[42:43], 0, v[128:129]
	s_addc_u32 s63, s43, 0
	s_add_i32 vcc_hi, vcc_hi, s82
	global_load_lds_dwordx4 v[228:229], off
	v_lshl_add_u64 v[230:231], s[62:63], 0, v[132:133]
	s_mov_b32 m0, vcc_hi
	v_lshl_add_u64 v[232:233], s[44:45], 0, v[130:131]
	global_load_lds_dwordx4 v[230:231], off
	v_lshl_add_u64 v[230:231], s[62:63], 0, v[128:129]
	s_add_i32 m0, vcc_hi, 0x2000
	s_nop 0
	global_load_lds_dwordx4 v[230:231], off
	v_lshl_add_u64 v[230:231], s[44:45], 0, v[134:135]
	s_mov_b32 m0, s83
	s_nop 0
	global_load_lds_dwordx4 v[230:231], off
	s_mov_b32 m0, s84
	s_nop 0
	global_load_lds_dwordx4 v[232:233], off
	s_waitcnt vmcnt(8)
	s_waitcnt lgkmcnt(0)
	s_barrier
	s_setprio 1
	v_mfma_f32_16x16x32_bf16 v[60:63], v[140:143], v[188:191], 0
	v_mfma_f32_16x16x32_bf16 v[56:59], v[148:151], v[188:191], 0
	v_mfma_f32_16x16x32_bf16 v[44:47], v[140:143], v[204:207], 0
	v_mfma_f32_16x16x32_bf16 v[40:43], v[148:151], v[204:207], 0
	v_mfma_f32_16x16x32_bf16 v[28:31], v[140:143], v[212:215], 0
	v_mfma_f32_16x16x32_bf16 v[24:27], v[148:151], v[212:215], 0
	v_mfma_f32_16x16x32_bf16 v[12:15], v[140:143], v[220:223], 0
	v_mfma_f32_16x16x32_bf16 v[8:11], v[148:151], v[220:223], 0
	v_mfma_f32_16x16x32_bf16 v[60:63], v[144:147], v[200:203], v[60:63]
	v_mfma_f32_16x16x32_bf16 v[56:59], v[168:171], v[200:203], v[56:59]
	v_mfma_f32_16x16x32_bf16 v[44:47], v[144:147], v[208:211], v[44:47]
	v_mfma_f32_16x16x32_bf16 v[40:43], v[168:171], v[208:211], v[40:43]
	v_mfma_f32_16x16x32_bf16 v[28:31], v[144:147], v[216:219], v[28:31]
	v_mfma_f32_16x16x32_bf16 v[24:27], v[168:171], v[216:219], v[24:27]
	v_mfma_f32_16x16x32_bf16 v[12:15], v[144:147], v[224:227], v[12:15]
	v_mfma_f32_16x16x32_bf16 v[8:11], v[168:171], v[224:227], v[8:11]
	s_setprio 0
	s_setprio 1
	v_mfma_f32_16x16x32_bf16 v[52:55], v[172:175], v[188:191], 0
	v_mfma_f32_16x16x32_bf16 v[48:51], v[180:183], v[188:191], 0
	v_mfma_f32_16x16x32_bf16 v[36:39], v[172:175], v[204:207], 0
	v_mfma_f32_16x16x32_bf16 v[32:35], v[180:183], v[204:207], 0
	v_mfma_f32_16x16x32_bf16 v[20:23], v[172:175], v[212:215], 0
	v_mfma_f32_16x16x32_bf16 v[16:19], v[180:183], v[212:215], 0
	v_mfma_f32_16x16x32_bf16 v[4:7], v[172:175], v[220:223], 0
	v_mfma_f32_16x16x32_bf16 v[0:3], v[180:183], v[220:223], 0
	v_mfma_f32_16x16x32_bf16 v[52:55], v[176:179], v[200:203], v[52:55]
	v_mfma_f32_16x16x32_bf16 v[48:51], v[184:187], v[200:203], v[48:51]
	v_mfma_f32_16x16x32_bf16 v[36:39], v[176:179], v[208:211], v[36:39]
	v_mfma_f32_16x16x32_bf16 v[32:35], v[184:187], v[208:211], v[32:35]
	v_mfma_f32_16x16x32_bf16 v[20:23], v[176:179], v[216:219], v[20:23]
	v_mfma_f32_16x16x32_bf16 v[16:19], v[184:187], v[216:219], v[16:19]
	v_mfma_f32_16x16x32_bf16 v[4:7], v[176:179], v[224:227], v[4:7]
	v_mfma_f32_16x16x32_bf16 v[0:3], v[184:187], v[224:227], v[0:3]
	s_setprio 0
	s_barrier
	s_add_i32 s62, 0, 0x18000
	v_add_u32_e32 v158, s62, v154
	s_add_i32 s63, 0, 0x1c000
	ds_read_b128 v[140:143], v158
	ds_read_b128 v[144:147], v158 offset:1024
	ds_read_b128 v[148:151], v158 offset:2048
	ds_read_b128 v[168:171], v158 offset:3072
	v_add_u32_e32 v158, s63, v154
	ds_read_b128 v[172:175], v158
	ds_read_b128 v[176:179], v158 offset:1024
	ds_read_b128 v[180:183], v158 offset:2048
	ds_read_b128 v[184:187], v158 offset:3072
	s_add_u32 s44, s44, 0x40000
	s_addc_u32 s45, s45, 0
	s_mov_b32 m0, s85
	v_lshl_add_u64 v[234:235], s[44:45], 0, v[134:135]
	ds_read_b128 v[188:191], v155 offset:32768
	ds_read_b128 v[200:203], v155 offset:33792
	ds_read_b128 v[204:207], v155 offset:34816
	ds_read_b128 v[208:211], v155 offset:35840
	ds_read_b128 v[212:215], v155 offset:36864
	ds_read_b128 v[216:219], v155 offset:37888
	ds_read_b128 v[220:223], v155 offset:38912
	ds_read_b128 v[224:227], v155 offset:39936
	global_load_lds_dwordx4 v[234:235], off
	v_lshl_add_u64 v[234:235], s[44:45], 0, v[130:131]
	s_mov_b32 m0, s86
	s_nop 0
	global_load_lds_dwordx4 v[234:235], off
	s_waitcnt vmcnt(8)
	s_waitcnt lgkmcnt(0)
	s_barrier
	s_setprio 1
	v_mfma_f32_16x16x32_bf16 v[124:127], v[140:143], v[188:191], v[124:127]
	v_mfma_f32_16x16x32_bf16 v[120:123], v[148:151], v[188:191], v[120:123]
	v_mfma_f32_16x16x32_bf16 v[108:111], v[140:143], v[204:207], v[108:111]
	v_mfma_f32_16x16x32_bf16 v[104:107], v[148:151], v[204:207], v[104:107]
	v_mfma_f32_16x16x32_bf16 v[92:95], v[140:143], v[212:215], v[92:95]
	v_mfma_f32_16x16x32_bf16 v[88:91], v[148:151], v[212:215], v[88:91]
	v_mfma_f32_16x16x32_bf16 v[76:79], v[140:143], v[220:223], v[76:79]
	v_mfma_f32_16x16x32_bf16 v[72:75], v[148:151], v[220:223], v[72:75]
	v_mfma_f32_16x16x32_bf16 v[124:127], v[144:147], v[200:203], v[124:127]
	v_mfma_f32_16x16x32_bf16 v[120:123], v[168:171], v[200:203], v[120:123]
	v_mfma_f32_16x16x32_bf16 v[108:111], v[144:147], v[208:211], v[108:111]
	v_mfma_f32_16x16x32_bf16 v[104:107], v[168:171], v[208:211], v[104:107]
	v_mfma_f32_16x16x32_bf16 v[92:95], v[144:147], v[216:219], v[92:95]
	v_mfma_f32_16x16x32_bf16 v[88:91], v[168:171], v[216:219], v[88:91]
	v_mfma_f32_16x16x32_bf16 v[76:79], v[144:147], v[224:227], v[76:79]
	v_mfma_f32_16x16x32_bf16 v[72:75], v[168:171], v[224:227], v[72:75]
	s_setprio 0
	s_setprio 1
	v_mfma_f32_16x16x32_bf16 v[116:119], v[172:175], v[188:191], v[116:119]
	v_mfma_f32_16x16x32_bf16 v[112:115], v[180:183], v[188:191], v[112:115]
	v_mfma_f32_16x16x32_bf16 v[100:103], v[172:175], v[204:207], v[100:103]
	v_mfma_f32_16x16x32_bf16 v[96:99], v[180:183], v[204:207], v[96:99]
	v_mfma_f32_16x16x32_bf16 v[84:87], v[172:175], v[212:215], v[84:87]
	v_mfma_f32_16x16x32_bf16 v[80:83], v[180:183], v[212:215], v[80:83]
	v_mfma_f32_16x16x32_bf16 v[68:71], v[172:175], v[220:223], v[68:71]
	v_mfma_f32_16x16x32_bf16 v[64:67], v[180:183], v[220:223], v[64:67]
	v_mfma_f32_16x16x32_bf16 v[116:119], v[176:179], v[200:203], v[116:119]
	v_mfma_f32_16x16x32_bf16 v[112:115], v[184:187], v[200:203], v[112:115]
	v_mfma_f32_16x16x32_bf16 v[100:103], v[176:179], v[208:211], v[100:103]
	v_mfma_f32_16x16x32_bf16 v[96:99], v[184:187], v[208:211], v[96:99]
	v_mfma_f32_16x16x32_bf16 v[84:87], v[176:179], v[216:219], v[84:87]
	v_mfma_f32_16x16x32_bf16 v[80:83], v[184:187], v[216:219], v[80:83]
	v_mfma_f32_16x16x32_bf16 v[68:71], v[176:179], v[224:227], v[68:71]
	v_mfma_f32_16x16x32_bf16 v[64:67], v[184:187], v[224:227], v[64:67]
	s_setprio 0
	s_barrier
	s_add_i32 s44, s62, s82
	v_lshl_add_u64 v[192:193], v[192:193], 0, s[14:15]
	s_mov_b32 m0, s44
	ds_read_b128 v[188:191], v155 offset:49152
	ds_read_b128 v[200:203], v155 offset:50176
	ds_read_b128 v[204:207], v155 offset:51200
	ds_read_b128 v[208:211], v155 offset:52224
	ds_read_b128 v[212:215], v155 offset:53248
	ds_read_b128 v[216:219], v155 offset:54272
	ds_read_b128 v[220:223], v155 offset:55296
	ds_read_b128 v[224:227], v155 offset:56320
	global_load_lds_dwordx4 v[192:193], off
	s_add_i32 m0, s44, 0x2000
	s_add_u32 s42, s42, 0x40080
	v_lshl_add_u64 v[192:193], v[228:229], 0, s[14:15]
	s_addc_u32 s43, s43, 0
	s_add_i32 s44, s63, s82
	global_load_lds_dwordx4 v[192:193], off
	v_lshl_add_u64 v[192:193], s[42:43], 0, v[132:133]
	s_mov_b32 m0, s44
	s_nop 0
	global_load_lds_dwordx4 v[192:193], off
	v_lshl_add_u64 v[192:193], s[42:43], 0, v[128:129]
	s_add_i32 m0, s44, 0x2000
	s_nop 0
	global_load_lds_dwordx4 v[192:193], off
	v_lshl_add_u64 v[192:193], v[230:231], 0, s[14:15]
	s_mov_b32 m0, s89
	s_nop 0
	global_load_lds_dwordx4 v[192:193], off
	v_lshl_add_u64 v[192:193], v[232:233], 0, s[14:15]
	s_mov_b32 m0, s90
	s_nop 0
	global_load_lds_dwordx4 v[192:193], off
	s_waitcnt vmcnt(8)
	s_waitcnt lgkmcnt(0)
	s_barrier
	s_setprio 1
	v_mfma_f32_16x16x32_bf16 v[60:63], v[140:143], v[188:191], v[60:63]
	v_mfma_f32_16x16x32_bf16 v[56:59], v[148:151], v[188:191], v[56:59]
	v_mfma_f32_16x16x32_bf16 v[44:47], v[140:143], v[204:207], v[44:47]
	v_mfma_f32_16x16x32_bf16 v[40:43], v[148:151], v[204:207], v[40:43]
	v_mfma_f32_16x16x32_bf16 v[28:31], v[140:143], v[212:215], v[28:31]
	v_mfma_f32_16x16x32_bf16 v[24:27], v[148:151], v[212:215], v[24:27]
	v_mfma_f32_16x16x32_bf16 v[12:15], v[140:143], v[220:223], v[12:15]
	v_mfma_f32_16x16x32_bf16 v[8:11], v[148:151], v[220:223], v[8:11]
	v_mfma_f32_16x16x32_bf16 v[60:63], v[144:147], v[200:203], v[60:63]
	v_mfma_f32_16x16x32_bf16 v[56:59], v[168:171], v[200:203], v[56:59]
	v_mfma_f32_16x16x32_bf16 v[44:47], v[144:147], v[208:211], v[44:47]
	v_mfma_f32_16x16x32_bf16 v[40:43], v[168:171], v[208:211], v[40:43]
	v_mfma_f32_16x16x32_bf16 v[28:31], v[144:147], v[216:219], v[28:31]
	v_mfma_f32_16x16x32_bf16 v[24:27], v[168:171], v[216:219], v[24:27]
	v_mfma_f32_16x16x32_bf16 v[12:15], v[144:147], v[224:227], v[12:15]
	v_mfma_f32_16x16x32_bf16 v[8:11], v[168:171], v[224:227], v[8:11]
	s_setprio 0
	s_setprio 1
	v_mfma_f32_16x16x32_bf16 v[52:55], v[172:175], v[188:191], v[52:55]
	v_mfma_f32_16x16x32_bf16 v[48:51], v[180:183], v[188:191], v[48:51]
	v_mfma_f32_16x16x32_bf16 v[36:39], v[172:175], v[204:207], v[36:39]
	v_mfma_f32_16x16x32_bf16 v[32:35], v[180:183], v[204:207], v[32:35]
	v_mfma_f32_16x16x32_bf16 v[20:23], v[172:175], v[212:215], v[20:23]
	v_mfma_f32_16x16x32_bf16 v[16:19], v[180:183], v[212:215], v[16:19]
	v_mfma_f32_16x16x32_bf16 v[4:7], v[172:175], v[220:223], v[4:7]
	v_mfma_f32_16x16x32_bf16 v[0:3], v[180:183], v[220:223], v[0:3]
	v_mfma_f32_16x16x32_bf16 v[52:55], v[176:179], v[200:203], v[52:55]
	v_mfma_f32_16x16x32_bf16 v[48:51], v[184:187], v[200:203], v[48:51]
	v_mfma_f32_16x16x32_bf16 v[36:39], v[176:179], v[208:211], v[36:39]
	v_mfma_f32_16x16x32_bf16 v[32:35], v[184:187], v[208:211], v[32:35]
	v_mfma_f32_16x16x32_bf16 v[20:23], v[176:179], v[216:219], v[20:23]
	v_mfma_f32_16x16x32_bf16 v[16:19], v[184:187], v[216:219], v[16:19]
	v_mfma_f32_16x16x32_bf16 v[4:7], v[176:179], v[224:227], v[4:7]
	v_mfma_f32_16x16x32_bf16 v[0:3], v[184:187], v[224:227], v[0:3]
	s_setprio 0
	s_barrier
	s_add_i32 vcc_lo, vcc_lo, 2
	s_add_u32 s40, s40, 0x100
	s_addc_u32 s41, s41, 0
	s_add_u32 s64, s64, 0x100
	s_addc_u32 s65, s65, 0

.LBB0_710:
	s_add_i32 s49, s49, 1
	s_mov_b64 s[26:27], s[4:5]
	s_mov_b32 s5, s0
	s_mov_b32 s38, s0
	s_mul_i32 s0, s49, s78
	s_mov_b64 s[28:29], s[2:3]
	s_add_i32 s2, s0, s8
	s_cmp_lt_i32 s2, 16
	s_mov_b32 s4, s41
	s_mov_b32 s39, s41
	s_cselect_b64 s[24:25], -1, 0
	s_ashr_i32 s0, s2, 1
	s_and_b32 s41, s2, 1
	s_and_b64 s[2:3], s[24:25], exec
	s_cselect_b32 s4, s41, s4
	s_cselect_b32 s2, s0, s5
	s_ashr_i32 s5, s4, 31
	s_lshl_b64 s[4:5], s[4:5], 19
	s_add_u32 s4, s37, s4
	s_addc_u32 s5, s40, s5
	s_and_b64 s[30:31], s[24:25], exec
	s_cselect_b32 s50, s5, s27
	s_cselect_b32 s51, s4, s26
	s_ashr_i32 s3, s2, 31
	s_lshl_b64 s[2:3], s[2:3], 19
	s_add_u32 s2, s34, s2
	s_addc_u32 s3, s35, s3
	s_and_b64 s[30:31], s[24:25], exec
	s_cselect_b32 s58, s3, s29
	s_cselect_b32 s59, s2, s28
	s_add_u32 s26, s26, 0x40080
	s_addc_u32 s27, s27, 0
	s_add_u32 s60, s28, 0x100
	s_addc_u32 s61, s29, 0
	s_mov_b32 s64, -2
	s_add_u32 s28, s26, 0xfffc0080
	s_addc_u32 s29, s27, -1
	s_add_i32 s62, 0, 0x10000
	s_cmp_eq_u32 s64, 12
	s_cselect_b32 s31, s50, s29
	s_cselect_b32 s30, s51, s28
	v_add_u32_e32 v144, s62, v148
	s_cselect_b32 s29, s58, s61
	s_cselect_b32 s28, s59, s60
	s_add_i32 s63, 0, 0x14000
	ds_read_b128 v[140:143], v144
	ds_read_b128 v[150:153], v144 offset:1024
	ds_read_b128 v[168:171], v144 offset:2048
	ds_read_b128 v[172:175], v144 offset:3072
	v_add_u32_e32 v144, s63, v148
	ds_read_b128 v[176:179], v144
	ds_read_b128 v[180:183], v144 offset:1024
	ds_read_b128 v[184:187], v144 offset:2048
	ds_read_b128 v[188:191], v144 offset:3072
	v_lshl_add_u64 v[144:145], s[26:27], 0, v[136:137]
	s_add_i32 m0, s1, 0xc000
	ds_read_b128 v[198:201], v149
	ds_read_b128 v[202:205], v149 offset:1024
	ds_read_b128 v[206:209], v149 offset:2048
	ds_read_b128 v[210:213], v149 offset:3072
	ds_read_b128 v[214:217], v149 offset:4096
	ds_read_b128 v[218:221], v149 offset:5120
	ds_read_b128 v[222:225], v149 offset:6144
	ds_read_b128 v[226:229], v149 offset:7168
	global_load_lds_dwordx4 v[144:145], off
	v_lshl_add_u64 v[144:145], s[26:27], 0, v[138:139]
	s_add_i32 m0, s1, 0xe000
	s_nop 0
	global_load_lds_dwordx4 v[144:145], off
	s_waitcnt vmcnt(8)
	s_waitcnt lgkmcnt(0)
	s_barrier
	s_setprio 1
	v_mfma_f32_16x16x32_bf16 v[124:127], v[140:143], v[198:201], 0
	v_mfma_f32_16x16x32_bf16 v[120:123], v[168:171], v[198:201], 0
	v_mfma_f32_16x16x32_bf16 v[108:111], v[140:143], v[206:209], 0
	v_mfma_f32_16x16x32_bf16 v[104:107], v[168:171], v[206:209], 0
	v_mfma_f32_16x16x32_bf16 v[92:95], v[140:143], v[214:217], 0
	v_mfma_f32_16x16x32_bf16 v[88:91], v[168:171], v[214:217], 0
	v_mfma_f32_16x16x32_bf16 v[76:79], v[140:143], v[222:225], 0
	v_mfma_f32_16x16x32_bf16 v[72:75], v[168:171], v[222:225], 0
	v_mfma_f32_16x16x32_bf16 v[124:127], v[150:153], v[202:205], v[124:127]
	v_mfma_f32_16x16x32_bf16 v[120:123], v[172:175], v[202:205], v[120:123]
	v_mfma_f32_16x16x32_bf16 v[108:111], v[150:153], v[210:213], v[108:111]
	v_mfma_f32_16x16x32_bf16 v[104:107], v[172:175], v[210:213], v[104:107]
	v_mfma_f32_16x16x32_bf16 v[92:95], v[150:153], v[218:221], v[92:95]
	v_mfma_f32_16x16x32_bf16 v[88:91], v[172:175], v[218:221], v[88:91]
	v_mfma_f32_16x16x32_bf16 v[76:79], v[150:153], v[226:229], v[76:79]
	v_mfma_f32_16x16x32_bf16 v[72:75], v[172:175], v[226:229], v[72:75]
	s_setprio 0
	s_setprio 1
	v_mfma_f32_16x16x32_bf16 v[116:119], v[176:179], v[198:201], 0
	v_mfma_f32_16x16x32_bf16 v[112:115], v[184:187], v[198:201], 0
	v_mfma_f32_16x16x32_bf16 v[100:103], v[176:179], v[206:209], 0
	v_mfma_f32_16x16x32_bf16 v[96:99], v[184:187], v[206:209], 0
	v_mfma_f32_16x16x32_bf16 v[84:87], v[176:179], v[214:217], 0
	v_mfma_f32_16x16x32_bf16 v[80:83], v[184:187], v[214:217], 0
	v_mfma_f32_16x16x32_bf16 v[68:71], v[176:179], v[222:225], 0
	v_mfma_f32_16x16x32_bf16 v[64:67], v[184:187], v[222:225], 0
	v_mfma_f32_16x16x32_bf16 v[116:119], v[180:183], v[202:205], v[116:119]
	v_mfma_f32_16x16x32_bf16 v[112:115], v[188:191], v[202:205], v[112:115]
	v_mfma_f32_16x16x32_bf16 v[100:103], v[180:183], v[210:213], v[100:103]
	v_mfma_f32_16x16x32_bf16 v[96:99], v[188:191], v[210:213], v[96:99]
	v_mfma_f32_16x16x32_bf16 v[84:87], v[180:183], v[218:221], v[84:87]
	v_mfma_f32_16x16x32_bf16 v[80:83], v[188:191], v[218:221], v[80:83]
	v_mfma_f32_16x16x32_bf16 v[68:71], v[180:183], v[226:229], v[68:71]
	v_mfma_f32_16x16x32_bf16 v[64:67], v[188:191], v[226:229], v[64:67]
	s_setprio 0
	s_barrier
	s_add_i32 s62, s62, s36
	v_lshl_add_u64 v[144:145], s[28:29], 0, v[132:133]
	s_mov_b32 m0, s62
	ds_read_b128 v[198:201], v149 offset:16384
	ds_read_b128 v[202:205], v149 offset:17408
	ds_read_b128 v[206:209], v149 offset:18432
	ds_read_b128 v[210:213], v149 offset:19456
	ds_read_b128 v[214:217], v149 offset:20480
	ds_read_b128 v[218:221], v149 offset:21504
	ds_read_b128 v[222:225], v149 offset:22528
	ds_read_b128 v[226:229], v149 offset:23552
	global_load_lds_dwordx4 v[144:145], off
	s_add_i32 m0, s62, 0x2000
	s_add_u32 s76, s28, 0x40000
	v_lshl_add_u64 v[154:155], s[28:29], 0, v[128:129]
	s_addc_u32 s77, s29, 0
	s_add_i32 s62, s63, s36
	global_load_lds_dwordx4 v[154:155], off
	v_lshl_add_u64 v[192:193], s[76:77], 0, v[132:133]
	s_mov_b32 m0, s62
	v_lshl_add_u64 v[230:231], s[30:31], 0, v[130:131]
	global_load_lds_dwordx4 v[192:193], off
	v_lshl_add_u64 v[192:193], s[76:77], 0, v[128:129]
	s_add_i32 m0, s62, 0x2000
	s_nop 0
	global_load_lds_dwordx4 v[192:193], off
	v_lshl_add_u64 v[192:193], s[30:31], 0, v[134:135]
	s_mov_b32 m0, s1
	s_nop 0
	global_load_lds_dwordx4 v[192:193], off
	s_mov_b32 m0, s42
	s_nop 0
	global_load_lds_dwordx4 v[230:231], off
	s_waitcnt vmcnt(8)
	s_waitcnt lgkmcnt(0)
	s_barrier
	s_setprio 1
	v_mfma_f32_16x16x32_bf16 v[60:63], v[140:143], v[198:201], 0
	v_mfma_f32_16x16x32_bf16 v[56:59], v[168:171], v[198:201], 0
	v_mfma_f32_16x16x32_bf16 v[44:47], v[140:143], v[206:209], 0
	v_mfma_f32_16x16x32_bf16 v[40:43], v[168:171], v[206:209], 0
	v_mfma_f32_16x16x32_bf16 v[28:31], v[140:143], v[214:217], 0
	v_mfma_f32_16x16x32_bf16 v[24:27], v[168:171], v[214:217], 0
	v_mfma_f32_16x16x32_bf16 v[12:15], v[140:143], v[222:225], 0
	v_mfma_f32_16x16x32_bf16 v[8:11], v[168:171], v[222:225], 0
	v_mfma_f32_16x16x32_bf16 v[60:63], v[150:153], v[202:205], v[60:63]
	v_mfma_f32_16x16x32_bf16 v[56:59], v[172:175], v[202:205], v[56:59]
	v_mfma_f32_16x16x32_bf16 v[44:47], v[150:153], v[210:213], v[44:47]
	v_mfma_f32_16x16x32_bf16 v[40:43], v[172:175], v[210:213], v[40:43]
	v_mfma_f32_16x16x32_bf16 v[28:31], v[150:153], v[218:221], v[28:31]
	v_mfma_f32_16x16x32_bf16 v[24:27], v[172:175], v[218:221], v[24:27]
	v_mfma_f32_16x16x32_bf16 v[12:15], v[150:153], v[226:229], v[12:15]
	v_mfma_f32_16x16x32_bf16 v[8:11], v[172:175], v[226:229], v[8:11]
	s_setprio 0
	s_setprio 1
	v_mfma_f32_16x16x32_bf16 v[52:55], v[176:179], v[198:201], 0
	v_mfma_f32_16x16x32_bf16 v[48:51], v[184:187], v[198:201], 0
	v_mfma_f32_16x16x32_bf16 v[36:39], v[176:179], v[206:209], 0
	v_mfma_f32_16x16x32_bf16 v[32:35], v[184:187], v[206:209], 0
	v_mfma_f32_16x16x32_bf16 v[20:23], v[176:179], v[214:217], 0
	v_mfma_f32_16x16x32_bf16 v[16:19], v[184:187], v[214:217], 0
	v_mfma_f32_16x16x32_bf16 v[4:7], v[176:179], v[222:225], 0
	v_mfma_f32_16x16x32_bf16 v[0:3], v[184:187], v[222:225], 0
	v_mfma_f32_16x16x32_bf16 v[52:55], v[180:183], v[202:205], v[52:55]
	v_mfma_f32_16x16x32_bf16 v[48:51], v[188:191], v[202:205], v[48:51]
	v_mfma_f32_16x16x32_bf16 v[36:39], v[180:183], v[210:213], v[36:39]
	v_mfma_f32_16x16x32_bf16 v[32:35], v[188:191], v[210:213], v[32:35]
	v_mfma_f32_16x16x32_bf16 v[20:23], v[180:183], v[218:221], v[20:23]
	v_mfma_f32_16x16x32_bf16 v[16:19], v[188:191], v[218:221], v[16:19]
	v_mfma_f32_16x16x32_bf16 v[4:7], v[180:183], v[226:229], v[4:7]
	v_mfma_f32_16x16x32_bf16 v[0:3], v[188:191], v[226:229], v[0:3]
	s_setprio 0
	s_barrier
	s_add_i32 s62, 0, 0x18000
	v_add_u32_e32 v158, s62, v148
	s_add_i32 s63, 0, 0x1c000
	ds_read_b128 v[140:143], v158
	ds_read_b128 v[150:153], v158 offset:1024
	ds_read_b128 v[168:171], v158 offset:2048
	ds_read_b128 v[172:175], v158 offset:3072
	v_add_u32_e32 v158, s63, v148
	ds_read_b128 v[176:179], v158
	ds_read_b128 v[180:183], v158 offset:1024
	ds_read_b128 v[184:187], v158 offset:2048
	ds_read_b128 v[188:191], v158 offset:3072
	s_add_u32 s30, s30, 0x40000
	s_addc_u32 s31, s31, 0
	s_mov_b32 m0, s43
	v_lshl_add_u64 v[232:233], s[30:31], 0, v[134:135]
	ds_read_b128 v[198:201], v149 offset:32768
	ds_read_b128 v[202:205], v149 offset:33792
	ds_read_b128 v[206:209], v149 offset:34816
	ds_read_b128 v[210:213], v149 offset:35840
	ds_read_b128 v[214:217], v149 offset:36864
	ds_read_b128 v[218:221], v149 offset:37888
	ds_read_b128 v[222:225], v149 offset:38912
	ds_read_b128 v[226:229], v149 offset:39936
	global_load_lds_dwordx4 v[232:233], off
	v_lshl_add_u64 v[232:233], s[30:31], 0, v[130:131]
	s_mov_b32 m0, s44
	s_nop 0
	global_load_lds_dwordx4 v[232:233], off
	s_waitcnt vmcnt(8)
	s_waitcnt lgkmcnt(0)
	s_barrier
	s_setprio 1
	v_mfma_f32_16x16x32_bf16 v[124:127], v[140:143], v[198:201], v[124:127]
	v_mfma_f32_16x16x32_bf16 v[120:123], v[168:171], v[198:201], v[120:123]
	v_mfma_f32_16x16x32_bf16 v[108:111], v[140:143], v[206:209], v[108:111]
	v_mfma_f32_16x16x32_bf16 v[104:107], v[168:171], v[206:209], v[104:107]
	v_mfma_f32_16x16x32_bf16 v[92:95], v[140:143], v[214:217], v[92:95]
	v_mfma_f32_16x16x32_bf16 v[88:91], v[168:171], v[214:217], v[88:91]
	v_mfma_f32_16x16x32_bf16 v[76:79], v[140:143], v[222:225], v[76:79]
	v_mfma_f32_16x16x32_bf16 v[72:75], v[168:171], v[222:225], v[72:75]
	v_mfma_f32_16x16x32_bf16 v[124:127], v[150:153], v[202:205], v[124:127]
	v_mfma_f32_16x16x32_bf16 v[120:123], v[172:175], v[202:205], v[120:123]
	v_mfma_f32_16x16x32_bf16 v[108:111], v[150:153], v[210:213], v[108:111]
	v_mfma_f32_16x16x32_bf16 v[104:107], v[172:175], v[210:213], v[104:107]
	v_mfma_f32_16x16x32_bf16 v[92:95], v[150:153], v[218:221], v[92:95]
	v_mfma_f32_16x16x32_bf16 v[88:91], v[172:175], v[218:221], v[88:91]
	v_mfma_f32_16x16x32_bf16 v[76:79], v[150:153], v[226:229], v[76:79]
	v_mfma_f32_16x16x32_bf16 v[72:75], v[172:175], v[226:229], v[72:75]
	s_setprio 0
	s_setprio 1
	v_mfma_f32_16x16x32_bf16 v[116:119], v[176:179], v[198:201], v[116:119]
	v_mfma_f32_16x16x32_bf16 v[112:115], v[184:187], v[198:201], v[112:115]
	v_mfma_f32_16x16x32_bf16 v[100:103], v[176:179], v[206:209], v[100:103]
	v_mfma_f32_16x16x32_bf16 v[96:99], v[184:187], v[206:209], v[96:99]
	v_mfma_f32_16x16x32_bf16 v[84:87], v[176:179], v[214:217], v[84:87]
	v_mfma_f32_16x16x32_bf16 v[80:83], v[184:187], v[214:217], v[80:83]
	v_mfma_f32_16x16x32_bf16 v[68:71], v[176:179], v[222:225], v[68:71]
	v_mfma_f32_16x16x32_bf16 v[64:67], v[184:187], v[222:225], v[64:67]
	v_mfma_f32_16x16x32_bf16 v[116:119], v[180:183], v[202:205], v[116:119]
	v_mfma_f32_16x16x32_bf16 v[112:115], v[188:191], v[202:205], v[112:115]
	v_mfma_f32_16x16x32_bf16 v[100:103], v[180:183], v[210:213], v[100:103]
	v_mfma_f32_16x16x32_bf16 v[96:99], v[188:191], v[210:213], v[96:99]
	v_mfma_f32_16x16x32_bf16 v[84:87], v[180:183], v[218:221], v[84:87]
	v_mfma_f32_16x16x32_bf16 v[80:83], v[188:191], v[218:221], v[80:83]
	v_mfma_f32_16x16x32_bf16 v[68:71], v[180:183], v[226:229], v[68:71]
	v_mfma_f32_16x16x32_bf16 v[64:67], v[188:191], v[226:229], v[64:67]
	s_setprio 0
	s_barrier
	s_add_i32 s30, s62, s36
	v_lshl_add_u64 v[144:145], v[144:145], 0, s[14:15]
	s_mov_b32 m0, s30
	ds_read_b128 v[198:201], v149 offset:49152
	ds_read_b128 v[202:205], v149 offset:50176
	ds_read_b128 v[206:209], v149 offset:51200
	ds_read_b128 v[210:213], v149 offset:52224
	ds_read_b128 v[214:217], v149 offset:53248
	ds_read_b128 v[218:221], v149 offset:54272
	ds_read_b128 v[222:225], v149 offset:55296
	ds_read_b128 v[226:229], v149 offset:56320
	global_load_lds_dwordx4 v[144:145], off
	s_add_i32 m0, s30, 0x2000
	s_add_u32 s28, s28, 0x40080
	v_lshl_add_u64 v[144:145], v[154:155], 0, s[14:15]
	s_addc_u32 s29, s29, 0
	s_add_i32 s30, s63, s36
	global_load_lds_dwordx4 v[144:145], off
	v_lshl_add_u64 v[144:145], s[28:29], 0, v[132:133]
	s_mov_b32 m0, s30
	s_nop 0
	global_load_lds_dwordx4 v[144:145], off
	v_lshl_add_u64 v[144:145], s[28:29], 0, v[128:129]
	s_add_i32 m0, s30, 0x2000
	s_nop 0
	global_load_lds_dwordx4 v[144:145], off
	v_lshl_add_u64 v[144:145], v[192:193], 0, s[14:15]
	s_mov_b32 m0, s47
	s_nop 0
	global_load_lds_dwordx4 v[144:145], off
	v_lshl_add_u64 v[144:145], v[230:231], 0, s[14:15]
	s_mov_b32 m0, s48
	s_nop 0
	global_load_lds_dwordx4 v[144:145], off
	s_waitcnt vmcnt(8)
	s_waitcnt lgkmcnt(0)
	s_barrier
	s_setprio 1
	v_mfma_f32_16x16x32_bf16 v[60:63], v[140:143], v[198:201], v[60:63]
	v_mfma_f32_16x16x32_bf16 v[56:59], v[168:171], v[198:201], v[56:59]
	v_mfma_f32_16x16x32_bf16 v[44:47], v[140:143], v[206:209], v[44:47]
	v_mfma_f32_16x16x32_bf16 v[40:43], v[168:171], v[206:209], v[40:43]
	v_mfma_f32_16x16x32_bf16 v[28:31], v[140:143], v[214:217], v[28:31]
	v_mfma_f32_16x16x32_bf16 v[24:27], v[168:171], v[214:217], v[24:27]
	v_mfma_f32_16x16x32_bf16 v[12:15], v[140:143], v[222:225], v[12:15]
	v_mfma_f32_16x16x32_bf16 v[8:11], v[168:171], v[222:225], v[8:11]
	v_mfma_f32_16x16x32_bf16 v[60:63], v[150:153], v[202:205], v[60:63]
	v_mfma_f32_16x16x32_bf16 v[56:59], v[172:175], v[202:205], v[56:59]
	v_mfma_f32_16x16x32_bf16 v[44:47], v[150:153], v[210:213], v[44:47]
	v_mfma_f32_16x16x32_bf16 v[40:43], v[172:175], v[210:213], v[40:43]
	v_mfma_f32_16x16x32_bf16 v[28:31], v[150:153], v[218:221], v[28:31]
	v_mfma_f32_16x16x32_bf16 v[24:27], v[172:175], v[218:221], v[24:27]
	v_mfma_f32_16x16x32_bf16 v[12:15], v[150:153], v[226:229], v[12:15]
	v_mfma_f32_16x16x32_bf16 v[8:11], v[172:175], v[226:229], v[8:11]
	s_setprio 0
	s_setprio 1
	v_mfma_f32_16x16x32_bf16 v[52:55], v[176:179], v[198:201], v[52:55]
	v_mfma_f32_16x16x32_bf16 v[48:51], v[184:187], v[198:201], v[48:51]
	v_mfma_f32_16x16x32_bf16 v[36:39], v[176:179], v[206:209], v[36:39]
	v_mfma_f32_16x16x32_bf16 v[32:35], v[184:187], v[206:209], v[32:35]
	v_mfma_f32_16x16x32_bf16 v[20:23], v[176:179], v[214:217], v[20:23]
	v_mfma_f32_16x16x32_bf16 v[16:19], v[184:187], v[214:217], v[16:19]
	v_mfma_f32_16x16x32_bf16 v[4:7], v[176:179], v[222:225], v[4:7]
	v_mfma_f32_16x16x32_bf16 v[0:3], v[184:187], v[222:225], v[0:3]
	v_mfma_f32_16x16x32_bf16 v[52:55], v[180:183], v[202:205], v[52:55]
	v_mfma_f32_16x16x32_bf16 v[48:51], v[188:191], v[202:205], v[48:51]
	v_mfma_f32_16x16x32_bf16 v[36:39], v[180:183], v[210:213], v[36:39]
	v_mfma_f32_16x16x32_bf16 v[32:35], v[188:191], v[210:213], v[32:35]
	v_mfma_f32_16x16x32_bf16 v[20:23], v[180:183], v[218:221], v[20:23]
	v_mfma_f32_16x16x32_bf16 v[16:19], v[188:191], v[218:221], v[16:19]
	v_mfma_f32_16x16x32_bf16 v[4:7], v[180:183], v[226:229], v[4:7]
	v_mfma_f32_16x16x32_bf16 v[0:3], v[188:191], v[226:229], v[0:3]
	s_setprio 0
	s_barrier
	s_add_i32 s64, s64, 2
	s_add_u32 s26, s26, 0x100
	s_addc_u32 s27, s27, 0
	s_add_u32 s60, s60, 0x100
	s_addc_u32 s61, s61, 0
